# poll back-off s_sleep 1 -> s_sleep 8 in every retry loop (fewer counter loads in flight beside the producers' atomics)
# speedup vs baseline: 1.0105x; 1.0105x over previous
; __device__ __forceinline__ unsigned xb_ld(unsigned* p)              { return __hip_atomic_load(p, __ATOMIC_RELAXED, __HIP_MEMORY_SCOPE_AGENT); }
; __device__ __forceinline__ void xcd_barrier_complete(unsigned* bar, unsigned x, unsigned& nloc, unsigned& nx) {
;     const unsigned G = gridDim.x * gridDim.y * gridDim.z;
;     unsigned sum, cnt, mine, sp = 0u;
;     for (;;) {
;         sum = 0u; cnt = 0u; mine = 0u;
; #pragma unroll
;         for (unsigned j = 0; j < 16; ++j) { const unsigned c = xb_ld(&bar[XB_XCNT(j)]); sum += c; cnt += (c > 0u) ? 1u : 0u; mine = (j == x) ? c : mine; }
;         if (sum == G) break;
;         __builtin_amdgcn_s_sleep(1);
;         if ((++sp & 255u) == 0u) { if (xb_ld(&bar[XB_TMO])) break; if (sp > XB_SPIN_CAP) { atomicAdd(&bar[XB_TMO], 1u); break; } }
;     }
;     nloc = mine > 0u ? mine : 1u; nx = cnt > 0u ? cnt : 1u;
; }
.LBB0_36:
	global_load_dword v16, v17, s[90:91] offset:1024 sc1
	global_load_dword v1, v17, s[90:91] offset:1280 sc1
	global_load_dword v2, v17, s[90:91] offset:1536 sc1
	global_load_dword v3, v17, s[90:91] offset:1792 sc1
	global_load_dword v4, v17, s[90:91] offset:2048 sc1
	global_load_dword v5, v17, s[90:91] offset:2304 sc1
	global_load_dword v6, v17, s[90:91] offset:2560 sc1
	global_load_dword v7, v17, s[90:91] offset:2816 sc1
	global_load_dword v8, v17, s[90:91] offset:3072 sc1
	global_load_dword v9, v17, s[90:91] offset:3328 sc1
	global_load_dword v10, v17, s[90:91] offset:3584 sc1
	global_load_dword v11, v17, s[90:91] offset:3840 sc1
	global_load_dword v12, v17, s[4:5] sc1
	global_load_dword v13, v17, s[8:9] sc1
	global_load_dword v14, v17, s[10:11] sc1
	global_load_dword v15, v17, s[12:13] sc1
	s_mov_b64 s[14:15], -1
	s_mov_b64 s[16:17], -1
	s_waitcnt vmcnt(14)
	v_add_u32_e32 v18, v1, v16
	s_waitcnt vmcnt(13)
	v_add_u32_e32 v18, v18, v2
	s_waitcnt vmcnt(12)
	v_add_u32_e32 v18, v18, v3
	s_waitcnt vmcnt(11)
	v_add_u32_e32 v18, v18, v4
	s_waitcnt vmcnt(10)
	v_add_u32_e32 v18, v18, v5
	s_waitcnt vmcnt(9)
	v_add_u32_e32 v18, v18, v6
	s_waitcnt vmcnt(8)
	v_add_u32_e32 v18, v18, v7
	s_waitcnt vmcnt(7)
	v_add_u32_e32 v18, v18, v8
	s_waitcnt vmcnt(6)
	v_add_u32_e32 v18, v18, v9
	s_waitcnt vmcnt(5)
	v_add_u32_e32 v18, v18, v10
	s_waitcnt vmcnt(4)
	v_add_u32_e32 v18, v18, v11
	s_waitcnt vmcnt(3)
	v_add_u32_e32 v18, v18, v12
	s_waitcnt vmcnt(2)
	v_add_u32_e32 v18, v18, v13
	s_waitcnt vmcnt(1)
	v_add_u32_e32 v18, v18, v14
	s_waitcnt vmcnt(0)
	v_add_u32_e32 v18, v18, v15
	v_cmp_eq_u32_e32 vcc, s3, v18
	s_cbranch_vccnz .LBB0_35
	s_and_b32 s14, s20, 0xff
	s_cmp_eq_u32 s14, 0
	s_mov_b64 s[14:15], -1
	s_mov_b64 s[18:19], -1
	s_sleep 8
	s_cbranch_scc0 .LBB0_40
	global_load_dword v18, v17, s[90:91] offset:512 sc1
	s_waitcnt vmcnt(0)
	v_cmp_eq_u32_e32 vcc, 0, v18
	s_cbranch_vccnz .LBB0_42
	s_mov_b64 s[18:19], 0

.LBB0_89:
	s_and_b32 s16, s3, 0xff
	s_mov_b64 s[14:15], -1
	s_cmp_lg_u32 s16, 0
	s_mov_b64 s[18:19], -1
	s_sleep 8
	s_cbranch_scc1 .LBB0_92
	global_load_dword v3, v2, s[90:91] offset:512 sc1
	s_waitcnt vmcnt(0)
	v_cmp_eq_u32_e32 vcc, 0, v3
	s_cbranch_vccnz .LBB0_94
	s_mov_b64 s[18:19], 0
	s_mov_b64 s[16:17], -1

.LBB0_157:
	s_and_b32 s10, s4, 0xff
	s_mov_b64 s[8:9], -1
	s_cmp_lg_u32 s10, 0
	s_mov_b64 s[12:13], -1
	s_sleep 8
	s_cbranch_scc0 .LBB0_160
	s_and_b64 vcc, exec, s[12:13]
	s_cbranch_vccz .LBB0_156

; __device__ __forceinline__ unsigned xb_ld(unsigned* p)              { return __hip_atomic_load(p, __ATOMIC_RELAXED, __HIP_MEMORY_SCOPE_AGENT); }
; __device__ __forceinline__ void xcd_barrier_complete(unsigned* bar, unsigned x, unsigned& nloc, unsigned& nx) {
;     const unsigned G = gridDim.x * gridDim.y * gridDim.z;
;     unsigned sum, cnt, mine, sp = 0u;
;     for (;;) {
;         sum = 0u; cnt = 0u; mine = 0u;
; #pragma unroll
;         for (unsigned j = 0; j < 16; ++j) { const unsigned c = xb_ld(&bar[XB_XCNT(j)]); sum += c; cnt += (c > 0u) ? 1u : 0u; mine = (j == x) ? c : mine; }
;         if (sum == G) break;
;         __builtin_amdgcn_s_sleep(1);
;         if ((++sp & 255u) == 0u) { if (xb_ld(&bar[XB_TMO])) break; if (sp > XB_SPIN_CAP) { atomicAdd(&bar[XB_TMO], 1u); break; } }
;     }
;     nloc = mine > 0u ? mine : 1u; nx = cnt > 0u ? cnt : 1u;
; }
.LBB0_270:
	global_load_dword v16, v17, s[90:91] offset:1024 sc1
	global_load_dword v1, v17, s[90:91] offset:1280 sc1
	global_load_dword v2, v17, s[90:91] offset:1536 sc1
	global_load_dword v3, v17, s[90:91] offset:1792 sc1
	global_load_dword v4, v17, s[90:91] offset:2048 sc1
	global_load_dword v5, v17, s[90:91] offset:2304 sc1
	global_load_dword v6, v17, s[90:91] offset:2560 sc1
	global_load_dword v7, v17, s[90:91] offset:2816 sc1
	global_load_dword v8, v17, s[90:91] offset:3072 sc1
	global_load_dword v9, v17, s[90:91] offset:3328 sc1
	global_load_dword v10, v17, s[90:91] offset:3584 sc1
	global_load_dword v11, v17, s[90:91] offset:3840 sc1
	global_load_dword v12, v17, s[4:5] sc1
	global_load_dword v13, v17, s[6:7] sc1
	global_load_dword v14, v17, s[8:9] sc1
	global_load_dword v15, v17, s[10:11] sc1
	s_mov_b64 s[12:13], -1
	s_mov_b64 s[14:15], -1
	s_waitcnt vmcnt(14)
	v_add_u32_e32 v18, v1, v16
	s_waitcnt vmcnt(13)
	v_add_u32_e32 v18, v18, v2
	s_waitcnt vmcnt(12)
	v_add_u32_e32 v18, v18, v3
	s_waitcnt vmcnt(11)
	v_add_u32_e32 v18, v18, v4
	s_waitcnt vmcnt(10)
	v_add_u32_e32 v18, v18, v5
	s_waitcnt vmcnt(9)
	v_add_u32_e32 v18, v18, v6
	s_waitcnt vmcnt(8)
	v_add_u32_e32 v18, v18, v7
	s_waitcnt vmcnt(7)
	v_add_u32_e32 v18, v18, v8
	s_waitcnt vmcnt(6)
	v_add_u32_e32 v18, v18, v9
	s_waitcnt vmcnt(5)
	v_add_u32_e32 v18, v18, v10
	s_waitcnt vmcnt(4)
	v_add_u32_e32 v18, v18, v11
	s_waitcnt vmcnt(3)
	v_add_u32_e32 v18, v18, v12
	s_waitcnt vmcnt(2)
	v_add_u32_e32 v18, v18, v13
	s_waitcnt vmcnt(1)
	v_add_u32_e32 v18, v18, v14
	s_waitcnt vmcnt(0)
	v_add_u32_e32 v18, v18, v15
	v_cmp_eq_u32_e32 vcc, s3, v18
	s_cbranch_vccnz .LBB0_269
	s_and_b32 s12, s18, 0xff
	s_cmp_eq_u32 s12, 0
	s_mov_b64 s[12:13], -1
	s_mov_b64 s[16:17], -1
	s_sleep 8
	s_cbranch_scc0 .LBB0_274
	global_load_dword v18, v17, s[90:91] offset:512 sc1
	s_waitcnt vmcnt(0)
	v_cmp_eq_u32_e32 vcc, 0, v18
	s_cbranch_vccnz .LBB0_276
	s_mov_b64 s[16:17], 0

.LBB0_362:
	s_and_b32 s8, s3, 0xff
	s_mov_b64 s[6:7], -1
	s_cmp_lg_u32 s8, 0
	s_mov_b64 s[10:11], -1
	s_sleep 8
	s_cbranch_scc0 .LBB0_365
	s_and_b64 vcc, exec, s[10:11]
	s_cbranch_vccz .LBB0_361

; __device__ __forceinline__ unsigned xb_ld(unsigned* p)              { return __hip_atomic_load(p, __ATOMIC_RELAXED, __HIP_MEMORY_SCOPE_AGENT); }
; __device__ __forceinline__ void xcd_barrier_complete(unsigned* bar, unsigned x, unsigned& nloc, unsigned& nx) {
;     const unsigned G = gridDim.x * gridDim.y * gridDim.z;
;     unsigned sum, cnt, mine, sp = 0u;
;     for (;;) {
;         sum = 0u; cnt = 0u; mine = 0u;
; #pragma unroll
;         for (unsigned j = 0; j < 16; ++j) { const unsigned c = xb_ld(&bar[XB_XCNT(j)]); sum += c; cnt += (c > 0u) ? 1u : 0u; mine = (j == x) ? c : mine; }
;         if (sum == G) break;
;         __builtin_amdgcn_s_sleep(1);
;         if ((++sp & 255u) == 0u) { if (xb_ld(&bar[XB_TMO])) break; if (sp > XB_SPIN_CAP) { atomicAdd(&bar[XB_TMO], 1u); break; } }
;     }
;     nloc = mine > 0u ? mine : 1u; nx = cnt > 0u ? cnt : 1u;
; }
.LBB0_384:
	global_load_dword v17, v18, s[90:91] offset:1024 sc1
	global_load_dword v2, v18, s[90:91] offset:1280 sc1
	global_load_dword v3, v18, s[90:91] offset:1536 sc1
	global_load_dword v4, v18, s[90:91] offset:1792 sc1
	global_load_dword v5, v18, s[90:91] offset:2048 sc1
	global_load_dword v6, v18, s[90:91] offset:2304 sc1
	global_load_dword v7, v18, s[90:91] offset:2560 sc1
	global_load_dword v8, v18, s[90:91] offset:2816 sc1
	global_load_dword v9, v18, s[90:91] offset:3072 sc1
	global_load_dword v10, v18, s[90:91] offset:3328 sc1
	global_load_dword v11, v18, s[90:91] offset:3584 sc1
	global_load_dword v12, v18, s[90:91] offset:3840 sc1
	global_load_dword v13, v18, s[4:5] sc1
	global_load_dword v14, v18, s[6:7] sc1
	global_load_dword v15, v18, s[8:9] sc1
	global_load_dword v16, v18, s[10:11] sc1
	s_mov_b64 s[12:13], -1
	s_mov_b64 s[14:15], -1
	s_waitcnt vmcnt(14)
	v_add_u32_e32 v19, v2, v17
	s_waitcnt vmcnt(13)
	v_add_u32_e32 v19, v19, v3
	s_waitcnt vmcnt(12)
	v_add_u32_e32 v19, v19, v4
	s_waitcnt vmcnt(11)
	v_add_u32_e32 v19, v19, v5
	s_waitcnt vmcnt(10)
	v_add_u32_e32 v19, v19, v6
	s_waitcnt vmcnt(9)
	v_add_u32_e32 v19, v19, v7
	s_waitcnt vmcnt(8)
	v_add_u32_e32 v19, v19, v8
	s_waitcnt vmcnt(7)
	v_add_u32_e32 v19, v19, v9
	s_waitcnt vmcnt(6)
	v_add_u32_e32 v19, v19, v10
	s_waitcnt vmcnt(5)
	v_add_u32_e32 v19, v19, v11
	s_waitcnt vmcnt(4)
	v_add_u32_e32 v19, v19, v12
	s_waitcnt vmcnt(3)
	v_add_u32_e32 v19, v19, v13
	s_waitcnt vmcnt(2)
	v_add_u32_e32 v19, v19, v14
	s_waitcnt vmcnt(1)
	v_add_u32_e32 v19, v19, v15
	s_waitcnt vmcnt(0)
	v_add_u32_e32 v19, v19, v16
	v_cmp_eq_u32_e32 vcc, s3, v19
	s_cbranch_vccnz .LBB0_383
	s_and_b32 s12, s18, 0xff
	s_cmp_eq_u32 s12, 0
	s_mov_b64 s[12:13], -1
	s_mov_b64 s[16:17], -1
	s_sleep 8
	s_cbranch_scc0 .LBB0_388
	global_load_dword v19, v18, s[90:91] offset:512 sc1
	s_waitcnt vmcnt(0)
	v_cmp_eq_u32_e32 vcc, 0, v19
	s_cbranch_vccnz .LBB0_390
	s_mov_b64 s[16:17], 0

; __device__ __forceinline__ unsigned xb_ld(unsigned* p)              { return __hip_atomic_load(p, __ATOMIC_RELAXED, __HIP_MEMORY_SCOPE_AGENT); }
; #define XB_SPIN(cond, bar) do { unsigned _sp = 0; while (cond) { __builtin_amdgcn_s_sleep(1); \
;     if ((++_sp & 255u) == 0u) { if (xb_ld(&(bar)[XB_TMO])) break; if (_sp > XB_SPIN_CAP) { atomicAdd(&(bar)[XB_TMO], 1u); break; } } } } while (0)
; __global__ void __launch_bounds__(NTHR, 2) k_main(Args a) {
;     ...
;           if (tid == 0) { pg8::Unit u; for (int i = 0; S.next(i, u); ++i) { unsigned* cw = &((unsigned*)ws)[10240 + 16 * u.pm]; XB_SPIN(xb_ld(cw) < 4u, (unsigned*)ws); }
.LBB0_490:
	s_and_b32 s10, s17, 0xff
	s_mov_b64 s[8:9], -1
	s_cmp_lg_u32 s10, 0
	s_mov_b64 s[12:13], -1
	s_sleep 8
	s_cbranch_scc0 .LBB0_493
	s_and_b64 vcc, exec, s[12:13]
	s_cbranch_vccz .LBB0_489

; __device__ __forceinline__ unsigned xb_ld(unsigned* p)              { return __hip_atomic_load(p, __ATOMIC_RELAXED, __HIP_MEMORY_SCOPE_AGENT); }
; #define XB_SPIN(cond, bar) do { unsigned _sp = 0; while (cond) { __builtin_amdgcn_s_sleep(1); \
;     if ((++_sp & 255u) == 0u) { if (xb_ld(&(bar)[XB_TMO])) break; if (_sp > XB_SPIN_CAP) { atomicAdd(&(bar)[XB_TMO], 1u); break; } } } } while (0)
; __global__ void __launch_bounds__(NTHR, 2) k_main(Args a) {
;     ...
;             if (tid == 0) { unsigned* cw = &((unsigned*)ws)[12288 + 16 * u.pm]; XB_SPIN(xb_ld(cw) < (unsigned)(D / 256), (unsigned*)ws);
.LBB0_553:
	s_and_b32 s28, s44, 0xff
	s_mov_b64 s[26:27], -1
	s_cmp_lg_u32 s28, 0
	s_mov_b64 s[30:31], -1
	s_sleep 8
	s_cbranch_scc0 .LBB0_556
	s_and_b64 vcc, exec, s[30:31]
	s_cbranch_vccz .LBB0_552

; __device__ __forceinline__ unsigned xb_ld(unsigned* p)              { return __hip_atomic_load(p, __ATOMIC_RELAXED, __HIP_MEMORY_SCOPE_AGENT); }
; #define XB_SPIN(cond, bar) do { unsigned _sp = 0; while (cond) { __builtin_amdgcn_s_sleep(1); \
;     if ((++_sp & 255u) == 0u) { if (xb_ld(&(bar)[XB_TMO])) break; if (_sp > XB_SPIN_CAP) { atomicAdd(&(bar)[XB_TMO], 1u); break; } } } } while (0)
; __global__ void __launch_bounds__(NTHR, 2) k_main(Args a) {
;     ...
;               XB_SPIN(xb_ld(&((unsigned*)ws)[14336]) < 256u, (unsigned*)ws);
.LBB0_600:
	s_and_b32 s10, s14, 0xff
	s_mov_b64 s[8:9], -1
	s_cmp_lg_u32 s10, 0
	s_mov_b64 s[12:13], -1
	s_sleep 8
	s_cbranch_scc0 .LBB0_603
	s_and_b64 vcc, exec, s[12:13]
	s_cbranch_vccz .LBB0_599

; __device__ __forceinline__ unsigned xb_ld(unsigned* p)              { return __hip_atomic_load(p, __ATOMIC_RELAXED, __HIP_MEMORY_SCOPE_AGENT); }
; #define XB_SPIN(cond, bar) do { unsigned _sp = 0; while (cond) { __builtin_amdgcn_s_sleep(1); \
;     if ((++_sp & 255u) == 0u) { if (xb_ld(&(bar)[XB_TMO])) break; if (_sp > XB_SPIN_CAP) { atomicAdd(&(bar)[XB_TMO], 1u); break; } } } } while (0)
; __global__ void __launch_bounds__(NTHR, 2) k_main(Args a) {
;     ...
;                 XB_SPIN(xb_ld(cw) < (unsigned)(D / 256), (unsigned*)ws);
.LBB0_652:
	s_and_b32 s42, s41, 0xff
	s_mov_b64 s[14:15], -1
	s_cmp_lg_u32 s42, 0
	s_mov_b64 s[44:45], -1
	s_sleep 8
	s_cbranch_scc0 .LBB0_655
	s_and_b64 vcc, exec, s[44:45]
	s_cbranch_vccz .LBB0_651

; __device__ __forceinline__ unsigned xb_ld(unsigned* p)              { return __hip_atomic_load(p, __ATOMIC_RELAXED, __HIP_MEMORY_SCOPE_AGENT); }
; #define XB_SPIN(cond, bar) do { unsigned _sp = 0; while (cond) { __builtin_amdgcn_s_sleep(1); \
;     if ((++_sp & 255u) == 0u) { if (xb_ld(&(bar)[XB_TMO])) break; if (_sp > XB_SPIN_CAP) { atomicAdd(&(bar)[XB_TMO], 1u); break; } } } } while (0)
; __global__ void __launch_bounds__(NTHR, 2) k_main(Args a) {
;     ...
;             if (tid == 0) XB_SPIN(xb_ld(&((unsigned*)ws)[14400]) < (unsigned)((T / 256) * (D / 256)), (unsigned*)ws);
.LBB0_682:
	s_and_b32 s14, s41, 0xff
	s_mov_b64 s[12:13], -1
	s_cmp_lg_u32 s14, 0
	s_mov_b64 s[42:43], -1
	s_sleep 8
	s_cbranch_scc0 .LBB0_685
	s_and_b64 vcc, exec, s[42:43]
	s_cbranch_vccz .LBB0_681
